# v093 + wave-major item distribution in the P0 weight-conversion loop (last partial round spread over all workgroups)
# speedup vs baseline: 1.0028x; 1.0028x over previous
; #define LAS __attribute__((address_space(3)))
; __device__ __forceinline__ void p0_weights(KAP a, LAS unsigned char* lds, int gw, int NGW, int wave, int lane) {
;     LAS float* scr = (LAS float*)(lds + wave * 8704);
;     unsigned char* ws = a->ws;
;     constexpr int I_TOTAL = (2048 / 64) * (2624 / 32) + (512 / 64) * (1536 / 32) + (512 / 64) * (2048 / 32) + 2 * (2048 / 64) * (2048 / 32) + (2048 / 64) * (4608 / 32)
;                           + 4 * (2048 / 64) * (DFF / 32) + 2 * (DFF / 64) * (2048 / 32);
;     for (int item = gw; item < I_TOTAL; item += NGW) {
;         int it = item;
;         if (conv_matrix(it, a->in[13], 2048, 2624, (bf16*)(ws + WS_WIN0), 0, scr, lane)) continue;
.LBB0_36:
	v_mbcnt_lo_u32_b32 v2, -1, 0
	v_mbcnt_hi_u32_b32 v2, -1, v2
	s_lshl_b32 s5, s87, 3
	v_add_u32_e32 v0, s93, v2
	s_lshl_b32 s33, s74, 3
	v_readfirstlane_b32 s4, v0
	s_ashr_i32 s6, s4, 6
	s_lshl_b32 s98, s6, 8
	s_add_i32 s99, s98, s87
	v_writelane_b32 v253, s87, 2
	s_mov_b64 s[4:5], s[0:1]
	s_cmp_gt_i32 s99, 0x71bf
	s_cbranch_scc1 .LBB0_119
	s_load_dwordx2 s[8:9], s[4:5], 0xf0
	v_bfe_u32 v0, v2, 5, 1
	v_and_b32_e32 v28, 31, v2
	v_bfe_u32 v1, v2, 3, 3
	v_lshlrev_b32_e32 v2, 3, v2
	v_and_b32_e32 v2, 56, v2
	v_mov_b32_e32 v3, 0
	v_mul_u32_u24_e32 v6, 0x84, v2
	v_lshlrev_b32_e32 v2, 1, v2
	s_mul_i32 s10, s6, 0x2200
	s_waitcnt lgkmcnt(0)
	v_lshl_add_u64 v[22:23], s[8:9], 0, v[2:3]
	s_mov_b64 s[6:7], 0x100000
	s_add_i32 s11, s10, 0
	v_lshl_add_u64 v[4:5], v[22:23], 0, s[6:7]
	v_lshlrev_b32_e32 v2, 2, v1
	s_mov_b64 s[6:7], 0xc00000
	v_add3_u32 v44, s11, v6, v2
	v_lshl_add_u64 v[6:7], v[22:23], 0, s[6:7]
	s_mov_b64 s[6:7], 0xe00000
	v_lshl_add_u64 v[8:9], v[22:23], 0, s[6:7]
	s_mov_b64 s[6:7], 0x1000000
	v_lshl_add_u64 v[10:11], v[22:23], 0, s[6:7]
	s_mov_b64 s[6:7], 0x1800000
	v_lshl_add_u64 v[12:13], v[22:23], 0, s[6:7]
	s_mov_b64 s[6:7], 0x2a00000
	v_lshl_add_u64 v[14:15], v[22:23], 0, s[6:7]
	s_mov_b64 s[6:7], 0x3200000
	v_lshl_add_u64 v[16:17], v[22:23], 0, s[6:7]
	s_mov_b64 s[6:7], 0x5e00000
	v_lshl_add_u64 v[18:19], v[22:23], 0, s[6:7]
	s_mov_b64 s[6:7], 0x8a00000
	v_mul_u32_u24_e32 v2, 0x84, v0
	v_lshl_add_u64 v[20:21], v[22:23], 0, s[6:7]
	s_mov_b64 s[6:7], 0xa000000
	v_or_b32_e32 v2, s10, v2
	v_lshlrev_b32_e32 v24, 2, v28
	v_or_b32_e32 v45, 8, v1
	v_or_b32_e32 v46, 16, v1
	v_or_b32_e32 v47, 24, v1
	v_lshl_add_u64 v[22:23], v[22:23], 0, s[6:7]
	v_add3_u32 v48, v2, v24, 0
	v_mov_b32_e32 v25, v3
	v_or_b32_e32 v49, 14, v0
	v_or_b32_e32 v50, 12, v0
	v_or_b32_e32 v51, 10, v0
	v_or_b32_e32 v52, 8, v0
	v_or_b32_e32 v53, 6, v0
	v_or_b32_e32 v54, 4, v0
	v_or_b32_e32 v55, 2, v0
	v_or_b32_e32 v26, 0x2c00000, v24
	v_mov_b32_e32 v27, v3
	s_movk_i32 s23, 0x2900
	s_movk_i32 s24, 0x7fff
	s_mov_b32 s25, 0xffff0000
	s_movk_i32 s26, 0x1800
	s_movk_i32 s27, 0x4800
	s_movk_i32 s28, 0x1600
	s_movk_i32 s29, 0x5800
	s_mov_b64 s[6:7], 0x2c00000
	v_lshlrev_b32_e32 v2, 2, v28
	v_mov_b32_e32 v56, 0x4800
	v_mov_b32_e32 v57, 0x5800
	s_branch .LBB0_39
